# PE: rstd-table reduction moved behind the GEMM prologue's first DMA loads (loads issued early, one round trip), table's private barrier removed
# speedup vs baseline: 1.0078x; 1.0007x over previous
; #define PG8_STAGE(bufoff, gbase, voff) do { _Pragma("unroll") for (int _i = 0; _i < 2; ++_i) \
;         __builtin_amdgcn_global_load_lds((const unsigned*)((const char*)(gbase) + (voff)[_i]), (PG8_LAS unsigned*)(lds + (bufoff) + ldsw + _i * 8192), 16, 0, 0); } while (0)
; #define PG8_WAIT_V(n) asm volatile("s_waitcnt vmcnt(" #n ")" ::: "memory")
; #define PG8_BAR __builtin_amdgcn_s_barrier()
; template <class Epi, class Sched, bool ALIGN_EPI = false, bool SP2 = false>
; __device__ __forceinline__ void gemm_phase(PG8_LAS unsigned char* lds, const Gemm g, const Sched& S, const Epi& E) {
;     ...
;     if constexpr (SP2) {
;         PG8_STAGE(PG8_SB(0, 0), cB, voffB); PG8_STAGE(PG8_SB(0, 1), cB + hstepB, voffB); PG8_STAGE(PG8_SA(0, 0), cA, voffA); PG8_STAGE(PG8_SA(0, 1), cA + hstep, voffA);
;         if (wr == 1) PG8_BAR;
;         PG8_WAIT_V(2); PG8_BAR;
.LBB0_771:
	s_or_b64 exec, exec, s[44:45]
	v_readlane_b32 s6, v241, 13
	v_readlane_b32 s7, v241, 14
	s_and_b64 s[24:25], s[6:7], exec
	v_readlane_b32 s6, v241, 33
	v_readlane_b32 s7, v241, 34
	v_readlane_b32 s12, v238, 29
	v_readlane_b32 s13, v238, 30
	s_cselect_b32 s12, s6, s12
	v_readlane_b32 s6, v241, 15
	v_writelane_b32 v238, s12, 29
	v_readlane_b32 s7, v241, 16
	s_waitcnt vmcnt(0) lgkmcnt(0)
	v_writelane_b32 v238, s13, 30
	s_barrier
	s_and_saveexec_b64 s[44:45], s[6:7]
	s_cbranch_execz .LBB0_773
	v_readlane_b32 s6, v238, 29
	s_mov_b32 s12, s6
	s_ashr_i32 s13, s6, 31
	v_lshl_add_u64 v[204:205], s[42:43], 2, v[160:161]
	s_lshl_b64 s[24:25], s[12:13], 20
	v_lshl_add_u64 v[216:217], v[204:205], 0, s[24:25]
	global_load_dwordx4 v[204:207], v[216:217], off
	global_load_dwordx4 v[208:211], v[216:217], off offset:32
	global_load_dwordx4 v[212:215], v[216:217], off offset:16
	s_nop 0
	global_load_dwordx4 v[216:219], v[216:217], off offset:48
.LBB0_773:
	s_or_b64 exec, exec, s[44:45]
	v_readlane_b32 s6, v241, 13
	v_mov_b32_e32 v12, v0
	v_readlane_b32 s7, v241, 14
	s_andn2_b64 vcc, exec, s[6:7]
	v_readfirstlane_b32 s30, v12
	s_cbranch_vccnz .LBB0_789
	v_lshlrev_b32_e32 v2, 4, v12
	v_add_u32_e32 v3, 0x2000, v2
	v_ashrrev_i32_e32 v4, 31, v3
	v_lshrrev_b32_e32 v4, 22, v4
	v_add_u32_e32 v4, v3, v4
	v_ashrrev_i32_e32 v6, 10, v4
	v_mul_i32_i24_e32 v4, 0x400, v6
	v_sub_u32_e32 v3, v3, v4
	v_lshrrev_b32_e32 v4, 4, v3
	v_bitop3_b32 v3, v4, v3, 32 bitop3:0x6c
	v_ashrrev_i32_e32 v4, 31, v3
	v_lshrrev_b32_e32 v4, 26, v4
	v_add_u32_e32 v4, v3, v4
	v_lshlrev_b32_e32 v5, 3, v6
	v_ashrrev_i32_e32 v7, 6, v4
	v_and_b32_e32 v5, -16, v5
	v_add_u32_e32 v5, v7, v5
	v_and_b32_e32 v8, 3, v7
	s_mov_b32 s6, 0x1fffe0
	v_lshrrev_b32_e32 v9, 2, v5
	v_lshlrev_b32_e32 v10, 1, v5
	v_and_b32_e32 v4, 0xc0, v4
	v_and_or_b32 v8, v5, s6, v8
	v_and_b32_e32 v9, 4, v9
	v_and_b32_e32 v10, 24, v10
	v_sub_u32_e32 v3, v3, v4
	v_or3_b32 v9, v8, v9, v10
	v_lshlrev_b32_e32 v8, 5, v6
	v_ashrrev_i16_sdwa v3, v196, sext(v3) dst_sel:DWORD dst_unused:UNUSED_PAD src0_sel:DWORD src1_sel:BYTE_0
	v_and_b32_e32 v10, 32, v8
	v_bfe_i32 v8, v3, 0, 16
	v_add_lshl_u32 v3, v10, v8, 1
	v_lshl_add_u32 v132, v9, 11, v3
	v_lshl_add_u32 v134, v5, 11, v3
	v_bfe_i32 v3, v12, 27, 1
	v_lshrrev_b32_e32 v3, 22, v3
	v_add_u32_e32 v3, v2, v3
	v_and_b32_e32 v3, 0xfffffc00, v3
	v_sub_u32_e32 v2, v2, v3
	v_lshrrev_b32_e32 v3, 4, v2
	v_ashrrev_i32_e32 v4, 31, v12
	v_bitop3_b32 v2, v3, v2, 32 bitop3:0x6c
	v_lshrrev_b32_e32 v4, 26, v4
	v_ashrrev_i32_e32 v3, 31, v2
	v_add_u32_e32 v4, v12, v4
	v_lshrrev_b32_e32 v3, 26, v3
	v_ashrrev_i32_e32 v10, 6, v4
	v_add_u32_e32 v3, v2, v3
	v_lshlrev_b32_e32 v4, 3, v10
	v_ashrrev_i32_e32 v9, 6, v3
	v_and_b32_e32 v4, -16, v4
	v_add_u32_e32 v4, v9, v4
	v_and_b32_e32 v5, 3, v9
	v_lshrrev_b32_e32 v11, 2, v4
	v_lshlrev_b32_e32 v13, 1, v4
	v_and_b32_e32 v3, 0xc0, v3
	s_ashr_i32 s28, s30, 6
	v_and_or_b32 v5, v4, s6, v5
	v_and_b32_e32 v11, 4, v11
	v_and_b32_e32 v13, 24, v13
	v_sub_u32_e32 v2, v2, v3
	s_ashr_i32 s31, s30, 8
	s_lshl_b32 s23, s28, 10
	v_or3_b32 v5, v5, v11, v13
	v_lshlrev_b32_e32 v11, 5, v10
	v_ashrrev_i16_sdwa v2, v196, sext(v2) dst_sel:DWORD dst_unused:UNUSED_PAD src0_sel:DWORD src1_sel:BYTE_0
	v_readlane_b32 s6, v241, 29
	v_and_b32_e32 v13, 32, v11
	v_bfe_i32 v11, v2, 0, 16
	v_readlane_b32 s7, v241, 30
	s_add_u32 s66, s58, s6
	v_add_lshl_u32 v2, v13, v11, 1
	s_addc_u32 s67, s59, s7
	s_add_i32 s24, s23, 0
	v_lshl_add_u32 v136, v5, 11, v2
	s_add_i32 m0, s24, 0x10000
	v_readlane_b32 s6, v241, 35
	global_load_lds_dwordx4 v136, s[66:67]
	s_add_i32 m0, s24, 0x12000
	s_add_u32 s26, s66, 0x40000
	global_load_lds_dwordx4 v132, s[66:67]
	s_addc_u32 s27, s67, 0
	s_add_i32 m0, s24, 0x14000
	v_lshl_add_u32 v138, v4, 11, v2
	global_load_lds_dwordx4 v136, s[26:27]
	s_add_i32 m0, s24, 0x16000
	v_readlane_b32 s7, v241, 36
	global_load_lds_dwordx4 v132, s[26:27]
	s_mov_b32 m0, s24
	s_add_i32 s25, s24, 0x2000
	s_add_i32 s26, s24, 0x4000
	s_nop 0
	global_load_lds_dwordx4 v138, s[6:7]
	s_mov_b32 m0, s25
	s_add_i32 s27, s24, 0x6000
	global_load_lds_dwordx4 v134, s[6:7]
	v_readlane_b32 s6, v241, 37
	s_mov_b32 m0, s26
	v_readlane_b32 s7, v241, 38
	v_mov_b32_e32 v137, v66
	v_mov_b32_e32 v133, v66
	s_cmp_eq_u32 s31, 1
	v_lshl_add_u64 v[2:3], s[66:67], 0, v[136:137]
	s_cselect_b64 s[42:43], -1, 0
	global_load_lds_dwordx4 v138, s[6:7]
	s_mov_b32 m0, s27
	s_cmp_lg_u32 s31, 1
	global_load_lds_dwordx4 v134, s[6:7]
	v_lshl_add_u64 v[4:5], s[66:67], 0, v[132:133]
	s_waitcnt vmcnt(8)
	v_readlane_b32 s6, v241, 15
	v_readlane_b32 s7, v241, 16
	s_nop 1
	s_and_saveexec_b64 s[44:45], s[6:7]
	v_mov_b32_e32 v220, v204
	v_mov_b32_e32 v221, v208
	v_mov_b32_e32 v208, v205
	v_mov_b32_e32 v204, v206
	v_mov_b32_e32 v205, v210
	v_mov_b32_e32 v210, v207
	v_mov_b32_e32 v206, v212
	v_mov_b32_e32 v207, v216
	v_mov_b32_e32 v216, v213
	v_mov_b32_e32 v212, v214
	v_mov_b32_e32 v213, v218
	v_mov_b32_e32 v218, v215
	v_pk_add_f32 v[208:209], v[220:221], v[208:209]
	v_pk_add_f32 v[204:205], v[204:205], v[210:211]
	v_pk_add_f32 v[206:207], v[206:207], v[216:217]
	v_pk_add_f32 v[210:211], v[212:213], v[218:219]
	v_pk_add_f32 v[204:205], v[208:209], v[204:205]
	v_pk_add_f32 v[206:207], v[206:207], v[210:211]
	v_pk_add_f32 v[204:205], v[204:205], v[206:207]
	s_mov_b32 s6, 0x800000
	v_add_f32_e32 v204, v204, v205
	v_fmamk_f32 v204, v204, 0x3a800000, v195
	v_mul_f32_e32 v205, 0x4b800000, v204
	v_cmp_gt_f32_e32 vcc, s6, v204
	s_nop 1
	v_cndmask_b32_e32 v204, v204, v205, vcc
	v_rsq_f32_e32 v204, v204
	s_nop 0
	v_mul_f32_e32 v205, 0x45800000, v204
	v_cndmask_b32_e32 v204, v204, v205, vcc
	ds_write_b32 v1, v204
	s_or_b64 exec, exec, s[44:45]
	s_cmp_lg_u32 s31, 1
	s_cbranch_scc1 .LBB0_776
	s_barrier
